# v82 + MLA loops: PV-section hazard pad after the last score MFMA trimmed from 10 to 2 states (11 instruction slots already lie between producer and consumer; 13 >= the 12 required)
# baseline (speedup 1.0000x reference)
.LBB0_892:
	v_sub_co_u32_e64 v66, s[28:29], s4, 3
	s_and_b32 s21, s4, 1
	s_add_i32 s1, s4, 1
	v_readfirstlane_b32 s4, v66
	s_lshl_b64 s[36:37], s[4:5], 6
	s_and_b64 s[38:39], s[28:29], exec
	s_cselect_b32 s37, s15, s37
	s_cselect_b32 s36, s14, s36
	s_mul_i32 s39, s37, 0xc00
	s_mul_hi_u32 s40, s36, 0xc00
	s_cselect_b32 s4, s13, s23
	s_cselect_b32 s38, s12, s22
	s_add_i32 s40, s40, s39
	s_mul_i32 s39, s36, 0xc00
	s_add_u32 s38, s38, s39
	s_addc_u32 s39, s4, s40
	s_xor_b32 s4, s21, 1
	s_mulk_i32 s4, 0x6000
	s_add_i32 s4, s69, s4
	s_add_i32 m0, s4, 0x8000
	s_nop 0
	global_load_lds_dwordx4 v222, s[38:39]
	s_add_i32 m0, s4, 0xa000
	s_lshl_b64 s[36:37], s[36:37], 12
	global_load_lds_dwordx4 v223, s[38:39]
	s_add_i32 m0, s4, 0xc000
	s_and_b64 s[28:29], s[28:29], exec
	s_cselect_b32 s28, s24, s33
	s_cselect_b32 s4, s25, s35
	s_add_u32 s28, s28, s36
	s_addc_u32 s29, s4, s37
	s_lshl_b32 s4, s21, 14
	s_xor_b32 s36, s4, 0x4000
	s_add_i32 s36, s69, s36
	global_load_lds_dwordx4 v224, s[38:39]
	s_mov_b32 m0, s36
	s_mulk_i32 s21, 0x6000
	global_load_lds_dwordx4 v225, s[28:29]
	s_add_i32 m0, s36, 0x2000
	s_nop 0
	global_load_lds_dwordx4 v226, s[28:29]
	v_add_u32_e32 v70, s21, v179
	v_add_u32_e32 v71, v70, v178
	ds_read_b128 v[66:69], v71 offset:32768
	v_add_u32_e32 v153, v70, v180
	v_add_u32_e32 v155, v70, v181
	v_add_u32_e32 v157, v70, v182
	v_add_u32_e32 v159, v70, v183
	v_add_u32_e32 v193, v70, v184
	v_add_u32_e32 v198, v70, v185
	v_add_u32_e32 v199, v70, v186
	v_add_u32_e32 v200, v70, v187
	s_waitcnt lgkmcnt(0)
	v_mfma_f32_32x32x16_bf16 v[82:97], v[66:69], v[142:145], 0
	ds_read_b128 v[66:69], v153 offset:32768
	v_add_u32_e32 v201, v70, v188
	v_add_u32_e32 v202, v70, v189
	v_add_u32_e32 v203, v70, v190
	s_waitcnt lgkmcnt(0)
	v_mfma_f32_32x32x16_bf16 v[82:97], v[66:69], v[138:141], v[82:97]
	ds_read_b128 v[66:69], v155 offset:32768
	s_waitcnt lgkmcnt(0)
	v_mfma_f32_32x32x16_bf16 v[82:97], v[66:69], v[134:137], v[82:97]
	ds_read_b128 v[66:69], v157 offset:32768
	s_waitcnt lgkmcnt(0)
	v_mfma_f32_32x32x16_bf16 v[82:97], v[66:69], v[130:133], v[82:97]
	ds_read_b128 v[66:69], v159 offset:32768
	s_waitcnt lgkmcnt(0)
	v_mfma_f32_32x32x16_bf16 v[82:97], v[66:69], v[126:129], v[82:97]
	ds_read_b128 v[66:69], v193 offset:32768
	s_waitcnt lgkmcnt(0)
	v_mfma_f32_32x32x16_bf16 v[82:97], v[66:69], v[122:125], v[82:97]
	ds_read_b128 v[66:69], v198 offset:32768
	s_waitcnt lgkmcnt(0)
	v_mfma_f32_32x32x16_bf16 v[82:97], v[66:69], v[118:121], v[82:97]
	ds_read_b128 v[66:69], v199 offset:32768
	s_waitcnt lgkmcnt(0)
	v_mfma_f32_32x32x16_bf16 v[82:97], v[66:69], v[114:117], v[82:97]
	ds_read_b128 v[66:69], v200 offset:32768
	s_waitcnt lgkmcnt(0)
	v_mfma_f32_32x32x16_bf16 v[82:97], v[66:69], v[110:113], v[82:97]
	ds_read_b128 v[66:69], v201 offset:32768
	s_waitcnt lgkmcnt(0)
	v_mfma_f32_32x32x16_bf16 v[82:97], v[66:69], v[106:109], v[82:97]
	ds_read_b128 v[66:69], v202 offset:32768
	s_waitcnt lgkmcnt(0)
	v_mfma_f32_32x32x16_bf16 v[82:97], v[66:69], v[102:105], v[82:97]
	ds_read_b128 v[66:69], v203 offset:32768
	s_waitcnt lgkmcnt(0)
	v_mfma_f32_32x32x16_bf16 v[82:97], v[66:69], v[98:101], v[82:97]
	ds_read_b128 v[66:69], v71 offset:45056
	ds_read_b128 v[194:197], v153 offset:45056
	s_nop 9
	v_exp_f32_e32 v204, v88
	v_exp_f32_e32 v205, v89
	v_exp_f32_e32 v206, v90
	v_exp_f32_e32 v207, v91
	v_exp_f32_e32 v208, v92
	v_exp_f32_e32 v209, v93
	v_exp_f32_e32 v210, v94
	s_waitcnt lgkmcnt(0)
	v_mfma_f32_32x32x16_bf16 v[66:81], v[66:69], v[142:145], 0
	v_exp_f32_e32 v211, v95
	v_exp_f32_e32 v212, v96
	v_exp_f32_e32 v213, v97
	v_add_u32_e32 v153, s4, v176
	v_cvt_pk_bf16_f32 v88, v210, v211
	v_cvt_pk_bf16_f32 v89, v212, v213
	v_mfma_f32_32x32x16_bf16 v[66:81], v[194:197], v[138:141], v[66:81]
	ds_read_b128 v[194:197], v155 offset:45056
	v_exp_f32_e32 v155, v82
	s_waitcnt lgkmcnt(0)
	v_mfma_f32_32x32x16_bf16 v[66:81], v[194:197], v[134:137], v[66:81]
	ds_read_b128 v[194:197], v157 offset:45056
	v_exp_f32_e32 v157, v83
	s_nop 0
	v_cvt_pk_bf16_f32 v82, v155, v157
	s_waitcnt lgkmcnt(0)
	v_mfma_f32_32x32x16_bf16 v[66:81], v[194:197], v[130:133], v[66:81]
	ds_read_b128 v[194:197], v159 offset:45056
	v_exp_f32_e32 v159, v84
	s_waitcnt lgkmcnt(0)
	v_mfma_f32_32x32x16_bf16 v[66:81], v[194:197], v[126:129], v[66:81]
	ds_read_b128 v[194:197], v193 offset:45056
	v_exp_f32_e32 v193, v85
	v_cvt_pk_bf16_f32 v85, v204, v205
	v_cvt_pk_bf16_f32 v83, v159, v193
	s_waitcnt lgkmcnt(0)
	v_mfma_f32_32x32x16_bf16 v[66:81], v[194:197], v[122:125], v[66:81]
	ds_read_b128 v[194:197], v198 offset:45056
	s_waitcnt lgkmcnt(0)
	v_mfma_f32_32x32x16_bf16 v[66:81], v[194:197], v[118:121], v[66:81]
	ds_read_b128 v[194:197], v199 offset:45056
	s_waitcnt lgkmcnt(0)
	v_mfma_f32_32x32x16_bf16 v[66:81], v[194:197], v[114:117], v[66:81]
	ds_read_b128 v[194:197], v200 offset:45056
	s_waitcnt lgkmcnt(0)
	v_mfma_f32_32x32x16_bf16 v[66:81], v[194:197], v[110:113], v[66:81]
	ds_read_b128 v[194:197], v201 offset:45056
	s_waitcnt lgkmcnt(0)
	v_mfma_f32_32x32x16_bf16 v[66:81], v[194:197], v[106:109], v[66:81]
	ds_read_b128 v[194:197], v202 offset:45056
	v_exp_f32_e32 v202, v86
	v_cvt_pk_bf16_f32 v86, v206, v207
	s_waitcnt lgkmcnt(0)
	v_mfma_f32_32x32x16_bf16 v[66:81], v[194:197], v[102:105], v[66:81]
	ds_read_b128 v[194:197], v203 offset:45056
	v_exp_f32_e32 v203, v87
	v_cvt_pk_bf16_f32 v87, v208, v209
	v_cvt_pk_bf16_f32 v84, v202, v203
	s_waitcnt lgkmcnt(0)
	v_mfma_f32_32x32x16_bf16 v[66:81], v[194:197], v[98:101], v[66:81]
	ds_read_b64_tr_b16 v[90:91], v153 offset:0
	ds_read_b64_tr_b16 v[92:93], v153 offset:0x800
	ds_read_b64_tr_b16 v[94:95], v153 offset:0x1000
	ds_read_b64_tr_b16 v[96:97], v153 offset:0x1800
	ds_read_b64_tr_b16 v[194:195], v153 offset:0x200
	ds_read_b64_tr_b16 v[196:197], v153 offset:0xa00
	ds_read_b64_tr_b16 v[198:199], v153 offset:0x1200
	ds_read_b64_tr_b16 v[200:201], v153 offset:0x1a00
	s_waitcnt lgkmcnt(4)
	s_nop 0
	v_mfma_f32_32x32x16_bf16 v[2:17], v[82:85], v[90:93], v[2:17]
	s_nop 1
	v_exp_f32_e32 v214, v66
	v_exp_f32_e32 v215, v67
	v_exp_f32_e32 v216, v68
	v_exp_f32_e32 v217, v69
	v_mfma_f32_32x32x16_bf16 v[2:17], v[86:89], v[94:97], v[2:17]
	ds_read_b64_tr_b16 v[66:67], v153 offset:0x400
	ds_read_b64_tr_b16 v[68:69], v153 offset:0xc00
	ds_read_b64_tr_b16 v[90:91], v153 offset:0x1400
	ds_read_b64_tr_b16 v[92:93], v153 offset:0x1c00
	s_waitcnt lgkmcnt(4)
	v_mfma_f32_32x32x16_bf16 v[18:33], v[82:85], v[194:197], v[18:33]
	v_exp_f32_e32 v194, v70
	v_exp_f32_e32 v195, v71
	v_exp_f32_e32 v196, v72
	v_exp_f32_e32 v197, v73
	v_mfma_f32_32x32x16_bf16 v[18:33], v[86:89], v[198:201], v[18:33]
	ds_read_b64_tr_b16 v[70:71], v153 offset:0x600
	ds_read_b64_tr_b16 v[72:73], v153 offset:0xe00
	ds_read_b64_tr_b16 v[94:95], v153 offset:0x1600
	ds_read_b64_tr_b16 v[96:97], v153 offset:0x1e00
	s_waitcnt lgkmcnt(4)
	v_mfma_f32_32x32x16_bf16 v[34:49], v[82:85], v[66:69], v[34:49]
	v_exp_f32_e32 v198, v74
	v_exp_f32_e32 v199, v75
	v_exp_f32_e32 v200, v76
	v_exp_f32_e32 v201, v77
	v_mfma_f32_32x32x16_bf16 v[34:49], v[86:89], v[90:93], v[34:49]
	ds_read_b64_tr_b16 v[66:67], v153 offset:0x2000
	ds_read_b64_tr_b16 v[68:69], v153 offset:0x2800
	ds_read_b64_tr_b16 v[74:75], v153 offset:0x3000
	ds_read_b64_tr_b16 v[76:77], v153 offset:0x3800
	s_waitcnt lgkmcnt(4)
	v_mfma_f32_32x32x16_bf16 v[50:65], v[82:85], v[70:73], v[50:65]
	v_exp_f32_e32 v249, v78
	v_exp_f32_e32 v250, v79
	v_cvt_pk_bf16_f32 v72, v194, v195
	v_cvt_pk_bf16_f32 v73, v196, v197
	v_mfma_f32_32x32x16_bf16 v[50:65], v[86:89], v[94:97], v[50:65]
	v_exp_f32_e32 v251, v80
	v_exp_f32_e32 v248, v81
	v_cvt_pk_bf16_f32 v78, v198, v199
	v_cvt_pk_bf16_f32 v79, v200, v201
	v_cvt_pk_bf16_f32 v80, v249, v250
	v_cvt_pk_bf16_f32 v70, v214, v215
	v_cvt_pk_bf16_f32 v71, v216, v217
	v_cvt_pk_bf16_f32 v81, v251, v248
	ds_read_b64_tr_b16 v[82:83], v153 offset:0x2200
	ds_read_b64_tr_b16 v[84:85], v153 offset:0x2a00
	ds_read_b64_tr_b16 v[86:87], v153 offset:0x3200
	ds_read_b64_tr_b16 v[88:89], v153 offset:0x3a00
	s_waitcnt lgkmcnt(4)
	s_nop 0
	v_mfma_f32_32x32x16_bf16 v[2:17], v[70:73], v[66:69], v[2:17]
	v_add_f32_e32 v246, v155, v157
	v_add_f32_e32 v247, v214, v215
	v_add_f32_e32 v246, v246, v159
	v_add_f32_e32 v247, v247, v216
	v_mfma_f32_32x32x16_bf16 v[2:17], v[78:81], v[74:77], v[2:17]
	v_add_f32_e32 v246, v246, v193
	v_add_f32_e32 v247, v247, v217
	v_add_f32_e32 v246, v246, v202
	v_add_f32_e32 v247, v247, v194
	ds_read_b64_tr_b16 v[66:67], v153 offset:0x2400
	ds_read_b64_tr_b16 v[68:69], v153 offset:0x2c00
	ds_read_b64_tr_b16 v[74:75], v153 offset:0x3400
	ds_read_b64_tr_b16 v[76:77], v153 offset:0x3c00
	s_waitcnt lgkmcnt(4)
	v_mfma_f32_32x32x16_bf16 v[18:33], v[70:73], v[82:85], v[18:33]
	v_add_f32_e32 v246, v246, v203
	v_add_f32_e32 v247, v247, v195
	v_add_f32_e32 v246, v246, v204
	v_add_f32_e32 v247, v247, v196
	v_mfma_f32_32x32x16_bf16 v[18:33], v[78:81], v[86:89], v[18:33]
	v_add_f32_e32 v246, v246, v205
	v_add_f32_e32 v247, v247, v197
	v_add_f32_e32 v246, v246, v206
	v_add_f32_e32 v247, v247, v198
	ds_read_b64_tr_b16 v[82:83], v153 offset:0x2600
	ds_read_b64_tr_b16 v[84:85], v153 offset:0x2e00
	ds_read_b64_tr_b16 v[86:87], v153 offset:0x3600
	ds_read_b64_tr_b16 v[88:89], v153 offset:0x3e00
	s_waitcnt lgkmcnt(4)
	v_mfma_f32_32x32x16_bf16 v[34:49], v[70:73], v[66:69], v[34:49]
	v_add_f32_e32 v246, v246, v207
	v_add_f32_e32 v247, v247, v199
	v_add_f32_e32 v246, v246, v208
	v_add_f32_e32 v247, v247, v200
	v_mfma_f32_32x32x16_bf16 v[34:49], v[78:81], v[74:77], v[34:49]
	v_add_f32_e32 v246, v246, v209
	v_add_f32_e32 v247, v247, v201
	v_add_f32_e32 v246, v246, v210
	v_add_f32_e32 v247, v247, v249
	s_waitcnt lgkmcnt(0)
	v_mfma_f32_32x32x16_bf16 v[50:65], v[70:73], v[82:85], v[50:65]
	v_add_f32_e32 v246, v246, v211
	v_add_f32_e32 v247, v247, v250
	v_add_f32_e32 v246, v246, v212
	v_add_f32_e32 v247, v247, v251
	v_add_f32_e32 v246, v246, v213
	v_add_f32_e32 v247, v247, v248
	v_add_f32_e32 v246, v246, v247
	v_add_f32_e32 v151, v151, v246
	s_waitcnt vmcnt(0)
	s_add_u32 s14, s14, 64
	s_addc_u32 s15, s15, 0
	s_cmp_eq_u32 s0, s1
	s_mov_b32 s4, s1
	s_waitcnt vmcnt(0)
	s_barrier
	v_mfma_f32_32x32x16_bf16 v[50:65], v[78:81], v[86:89], v[50:65]
	s_cbranch_scc0 .LBB0_892
	s_lshl_b32 s1, s68, 2
	s_add_i32 s4, s1, 0
	s_and_b32 s0, s0, 1
	s_add_i32 s4, s4, 0x1e000
	s_mul_i32 s1, s0, 0x6000
	v_add_u32_e32 v70, s1, v179
	v_add_u32_e32 v71, v70, v178
	ds_read_b128 v[66:69], v71 offset:32768
	v_add_u32_e32 v153, v70, v180
	v_add_u32_e32 v155, v70, v181
	v_add_u32_e32 v157, v70, v182
	v_add_u32_e32 v159, v70, v183
	v_add_u32_e32 v160, v70, v184
	v_add_u32_e32 v161, v70, v185
	v_add_u32_e32 v162, v70, v186
	v_add_u32_e32 v163, v70, v187
	s_waitcnt lgkmcnt(0)
	v_mfma_f32_32x32x16_bf16 v[82:97], v[66:69], v[142:145], 0
	ds_read_b128 v[66:69], v153 offset:32768
	v_add_u32_e32 v170, v70, v188
	v_add_u32_e32 v171, v70, v189
	v_add_u32_e32 v172, v70, v190
	s_waitcnt lgkmcnt(0)
	v_mfma_f32_32x32x16_bf16 v[82:97], v[66:69], v[138:141], v[82:97]
	ds_read_b128 v[66:69], v155 offset:32768
	s_waitcnt lgkmcnt(0)
	v_mfma_f32_32x32x16_bf16 v[82:97], v[66:69], v[134:137], v[82:97]
	ds_read_b128 v[66:69], v157 offset:32768
	s_waitcnt lgkmcnt(0)
	v_mfma_f32_32x32x16_bf16 v[82:97], v[66:69], v[130:133], v[82:97]
	ds_read_b128 v[66:69], v159 offset:32768
	s_waitcnt lgkmcnt(0)
	v_mfma_f32_32x32x16_bf16 v[82:97], v[66:69], v[126:129], v[82:97]
	ds_read_b128 v[66:69], v160 offset:32768
	s_waitcnt lgkmcnt(0)
	v_mfma_f32_32x32x16_bf16 v[82:97], v[66:69], v[122:125], v[82:97]
	ds_read_b128 v[66:69], v161 offset:32768
	s_waitcnt lgkmcnt(0)
	v_mfma_f32_32x32x16_bf16 v[82:97], v[66:69], v[118:121], v[82:97]
	ds_read_b128 v[66:69], v162 offset:32768
	s_waitcnt lgkmcnt(0)
	v_mfma_f32_32x32x16_bf16 v[82:97], v[66:69], v[114:117], v[82:97]
	ds_read_b128 v[66:69], v163 offset:32768
	s_waitcnt lgkmcnt(0)
	v_mfma_f32_32x32x16_bf16 v[82:97], v[66:69], v[110:113], v[82:97]
	ds_read_b128 v[66:69], v170 offset:32768
	s_waitcnt lgkmcnt(0)
	v_mfma_f32_32x32x16_bf16 v[82:97], v[66:69], v[106:109], v[82:97]
	ds_read_b128 v[66:69], v171 offset:32768
	s_waitcnt lgkmcnt(0)
	v_mfma_f32_32x32x16_bf16 v[82:97], v[66:69], v[102:105], v[82:97]
	ds_read_b128 v[66:69], v172 offset:32768
	s_waitcnt lgkmcnt(0)
	v_mfma_f32_32x32x16_bf16 v[82:97], v[66:69], v[98:101], v[82:97]
	ds_read_b128 v[66:69], v71 offset:45056
	s_waitcnt lgkmcnt(0)
	v_mfma_f32_32x32x16_bf16 v[66:81], v[66:69], v[142:145], 0
	ds_read_b128 v[142:145], v153 offset:45056
	s_waitcnt lgkmcnt(0)
	v_mfma_f32_32x32x16_bf16 v[66:81], v[142:145], v[138:141], v[66:81]
	ds_read_b128 v[138:141], v155 offset:45056
	s_waitcnt lgkmcnt(0)
	v_mfma_f32_32x32x16_bf16 v[66:81], v[138:141], v[134:137], v[66:81]
	ds_read_b128 v[134:137], v157 offset:45056
	s_waitcnt lgkmcnt(0)
	v_mfma_f32_32x32x16_bf16 v[66:81], v[134:137], v[130:133], v[66:81]
	ds_read_b128 v[130:133], v159 offset:45056
	s_waitcnt lgkmcnt(0)
	v_mfma_f32_32x32x16_bf16 v[66:81], v[130:133], v[126:129], v[66:81]
	ds_read_b128 v[126:129], v160 offset:45056
	s_waitcnt lgkmcnt(0)
	v_mfma_f32_32x32x16_bf16 v[66:81], v[126:129], v[122:125], v[66:81]
	ds_read_b128 v[122:125], v161 offset:45056
	s_waitcnt lgkmcnt(0)
	v_mfma_f32_32x32x16_bf16 v[66:81], v[122:125], v[118:121], v[66:81]
	ds_read_b128 v[118:121], v162 offset:45056
	v_exp_f32_e32 v122, v97
	s_waitcnt lgkmcnt(0)
	v_mfma_f32_32x32x16_bf16 v[66:81], v[118:121], v[114:117], v[66:81]
	ds_read_b128 v[114:117], v163 offset:45056
	v_exp_f32_e32 v118, v93
	v_exp_f32_e32 v119, v94
	v_exp_f32_e32 v120, v95
	v_exp_f32_e32 v121, v96
	s_waitcnt lgkmcnt(0)
	v_mfma_f32_32x32x16_bf16 v[66:81], v[114:117], v[110:113], v[66:81]
	ds_read_b128 v[110:113], v170 offset:45056
	v_exp_f32_e32 v114, v89
	v_exp_f32_e32 v115, v90
	v_exp_f32_e32 v116, v91
	v_exp_f32_e32 v117, v92
	v_cvt_pk_bf16_f32 v89, v121, v122
	s_waitcnt lgkmcnt(0)
	v_mfma_f32_32x32x16_bf16 v[66:81], v[110:113], v[106:109], v[66:81]
	ds_read_b128 v[106:109], v171 offset:45056
	v_exp_f32_e32 v110, v85
	v_exp_f32_e32 v111, v86
	v_exp_f32_e32 v112, v87
	v_exp_f32_e32 v113, v88
	v_cvt_pk_bf16_f32 v86, v115, v116
	v_cvt_pk_bf16_f32 v87, v117, v118
	s_waitcnt lgkmcnt(0)
	v_mfma_f32_32x32x16_bf16 v[66:81], v[106:109], v[102:105], v[66:81]
	ds_read_b128 v[102:105], v172 offset:45056
	v_exp_f32_e32 v107, v82
	v_exp_f32_e32 v108, v83
	v_exp_f32_e32 v109, v84
	v_cvt_pk_bf16_f32 v84, v111, v112
	v_cvt_pk_bf16_f32 v85, v113, v114
	v_cvt_pk_bf16_f32 v82, v107, v108
	s_waitcnt lgkmcnt(0)
	v_mfma_f32_32x32x16_bf16 v[66:81], v[102:105], v[98:101], v[66:81]
	v_cvt_pk_bf16_f32 v83, v109, v110
	v_cvt_pk_bf16_f32 v88, v119, v120
	v_lshl_add_u32 v106, s0, 14, v176
	ds_read_b64_tr_b16 v[90:91], v106 offset:0
	ds_read_b64_tr_b16 v[92:93], v106 offset:0x800
	ds_read_b64_tr_b16 v[94:95], v106 offset:0x1000
	ds_read_b64_tr_b16 v[96:97], v106 offset:0x1800
	ds_read_b64_tr_b16 v[98:99], v106 offset:0x200
	ds_read_b64_tr_b16 v[100:101], v106 offset:0xa00
	ds_read_b64_tr_b16 v[102:103], v106 offset:0x1200
	ds_read_b64_tr_b16 v[104:105], v106 offset:0x1a00
	s_waitcnt lgkmcnt(4)
	s_nop 0
	v_mfma_f32_32x32x16_bf16 v[2:17], v[82:85], v[90:93], v[2:17]
	s_nop 2
	v_exp_f32_e32 v123, v66
	v_exp_f32_e32 v124, v67
	v_exp_f32_e32 v125, v68
	v_exp_f32_e32 v126, v69
	v_mfma_f32_32x32x16_bf16 v[2:17], v[86:89], v[94:97], v[2:17]
	ds_read_b64_tr_b16 v[66:67], v106 offset:0x400
	ds_read_b64_tr_b16 v[68:69], v106 offset:0xc00
	ds_read_b64_tr_b16 v[90:91], v106 offset:0x1400
	ds_read_b64_tr_b16 v[92:93], v106 offset:0x1c00
	s_waitcnt lgkmcnt(4)
	v_mfma_f32_32x32x16_bf16 v[18:33], v[82:85], v[98:101], v[18:33]
	v_exp_f32_e32 v98, v70
	v_exp_f32_e32 v99, v71
	v_exp_f32_e32 v100, v72
	v_exp_f32_e32 v101, v73
	v_mfma_f32_32x32x16_bf16 v[18:33], v[86:89], v[102:105], v[18:33]
	ds_read_b64_tr_b16 v[70:71], v106 offset:0x600
	ds_read_b64_tr_b16 v[72:73], v106 offset:0xe00
	ds_read_b64_tr_b16 v[94:95], v106 offset:0x1600
	ds_read_b64_tr_b16 v[96:97], v106 offset:0x1e00
	s_waitcnt lgkmcnt(4)
	v_mfma_f32_32x32x16_bf16 v[34:49], v[82:85], v[66:69], v[34:49]
	v_exp_f32_e32 v102, v74
	v_exp_f32_e32 v103, v75
	v_exp_f32_e32 v104, v76
	v_exp_f32_e32 v105, v77
	v_mfma_f32_32x32x16_bf16 v[34:49], v[86:89], v[90:93], v[34:49]
	ds_read_b64_tr_b16 v[74:75], v106 offset:0x2000
	ds_read_b64_tr_b16 v[76:77], v106 offset:0x2800
	ds_read_b64_tr_b16 v[90:91], v106 offset:0x3000
	ds_read_b64_tr_b16 v[92:93], v106 offset:0x3800
	s_waitcnt lgkmcnt(4)
	v_add_f32_e32 v66, v107, v108
	v_add_f32_e32 v67, v123, v124
	v_mfma_f32_32x32x16_bf16 v[50:65], v[82:85], v[70:73], v[50:65]
	v_add_f32_e32 v66, v66, v109
	v_add_f32_e32 v67, v67, v125
	v_exp_f32_e32 v127, v78
	v_add_f32_e32 v66, v66, v110
	v_add_f32_e32 v67, v67, v126
	v_exp_f32_e32 v128, v79
	v_add_f32_e32 v66, v66, v111
	v_add_f32_e32 v67, v67, v98
	v_mfma_f32_32x32x16_bf16 v[50:65], v[86:89], v[94:97], v[50:65]
	v_add_f32_e32 v66, v66, v112
	v_add_f32_e32 v67, v67, v99
	v_exp_f32_e32 v129, v80
	v_add_f32_e32 v66, v66, v113
	v_add_f32_e32 v67, v67, v100
	v_exp_f32_e32 v81, v81
	v_add_f32_e32 v66, v66, v114
	v_add_f32_e32 v67, v67, v101
	v_cvt_pk_bf16_f32 v68, v123, v124
	v_add_f32_e32 v66, v66, v115
	v_add_f32_e32 v67, v67, v102
	v_cvt_pk_bf16_f32 v69, v125, v126
	v_add_f32_e32 v66, v66, v116
	v_add_f32_e32 v67, v67, v103
	v_cvt_pk_bf16_f32 v70, v98, v99
	v_add_f32_e32 v66, v66, v117
	v_add_f32_e32 v67, v67, v104
	v_cvt_pk_bf16_f32 v71, v100, v101
	v_add_f32_e32 v66, v66, v118
	v_add_f32_e32 v67, v67, v105
	v_cvt_pk_bf16_f32 v78, v102, v103
	v_add_f32_e32 v66, v66, v119
	v_add_f32_e32 v67, v67, v127
	v_cvt_pk_bf16_f32 v79, v104, v105
	v_add_f32_e32 v66, v66, v120
	v_add_f32_e32 v67, v67, v128
	v_cvt_pk_bf16_f32 v80, v127, v128
	v_add_f32_e32 v66, v66, v121
	v_add_f32_e32 v67, v67, v129
	v_add_f32_e32 v66, v66, v122
	v_add_f32_e32 v67, v67, v81
	v_cvt_pk_bf16_f32 v81, v129, v81
	v_add_f32_e32 v66, v66, v67
	v_add_f32_e32 v66, v151, v66
	v_mov_b32_e32 v67, v66
	s_nop 1
	v_permlane32_swap_b32_e32 v66, v67
	ds_read_b64_tr_b16 v[82:83], v106 offset:0x2200
	ds_read_b64_tr_b16 v[84:85], v106 offset:0x2a00
	ds_read_b64_tr_b16 v[86:87], v106 offset:0x3200
	ds_read_b64_tr_b16 v[88:89], v106 offset:0x3a00
	s_waitcnt lgkmcnt(4)
	v_mfma_f32_32x32x16_bf16 v[2:17], v[68:71], v[74:77], v[2:17]
	s_nop 0
	v_mfma_f32_32x32x16_bf16 v[2:17], v[78:81], v[90:93], v[2:17]
	ds_read_b64_tr_b16 v[72:73], v106 offset:0x2400
	ds_read_b64_tr_b16 v[74:75], v106 offset:0x2c00
	ds_read_b64_tr_b16 v[90:91], v106 offset:0x3400
	ds_read_b64_tr_b16 v[92:93], v106 offset:0x3c00
	s_waitcnt lgkmcnt(4)
	v_mfma_f32_32x32x16_bf16 v[18:33], v[68:71], v[82:85], v[18:33]
	v_mfma_f32_32x32x16_bf16 v[18:33], v[78:81], v[86:89], v[18:33]
	ds_read_b64_tr_b16 v[82:83], v106 offset:0x2600
	ds_read_b64_tr_b16 v[84:85], v106 offset:0x2e00
	ds_read_b64_tr_b16 v[86:87], v106 offset:0x3600
	ds_read_b64_tr_b16 v[88:89], v106 offset:0x3e00
	s_waitcnt lgkmcnt(4)
	v_mfma_f32_32x32x16_bf16 v[34:49], v[68:71], v[72:75], v[34:49]
	v_mfma_f32_32x32x16_bf16 v[34:49], v[78:81], v[90:93], v[34:49]
	s_waitcnt lgkmcnt(0)
	v_mfma_f32_32x32x16_bf16 v[50:65], v[68:71], v[82:85], v[50:65]
	s_waitcnt vmcnt(0)
	s_barrier
	v_mfma_f32_32x32x16_bf16 v[50:65], v[78:81], v[86:89], v[50:65]
	s_and_saveexec_b64 s[0:1], s[2:3]
	s_cbranch_execz .LBB0_886
	v_add_f32_e32 v66, v66, v67
	v_lshl_add_u32 v68, v1, 2, s4
	ds_write_b32 v68, v66
	s_branch .LBB0_886

.LBB0_2312:
	v_add_co_u32_e64 v66, s[14:15], s4, 3
	s_nop 0
	v_readfirstlane_b32 s21, v66
	s_and_b32 s21, s21, 1
	s_lshl_b64 s[28:29], s[4:5], 6
	s_and_b64 s[40:41], s[14:15], exec
	s_cselect_b32 s29, s1, s29
	s_cselect_b32 s28, s0, s28
	s_mul_i32 s42, s29, 0xc00
	s_mul_hi_u32 s43, s28, 0xc00
	s_cselect_b32 s41, s13, s39
	s_cselect_b32 s40, s12, s38
	s_add_i32 s43, s43, s42
	s_mul_i32 s42, s28, 0xc00
	s_add_u32 s40, s40, s42
	s_addc_u32 s41, s41, s43
	s_xor_b32 s42, s21, 1
	s_mulk_i32 s42, 0x6000
	s_add_i32 s42, s53, s42
	s_add_i32 m0, s42, 0x8000
	s_nop 0
	global_load_lds_dwordx4 v238, s[40:41]
	s_add_i32 m0, s42, 0xa000
	s_lshl_b64 s[28:29], s[28:29], 12
	global_load_lds_dwordx4 v239, s[40:41]
	s_add_i32 m0, s42, 0xc000
	s_and_b64 s[14:15], s[14:15], exec
	s_cselect_b32 s14, s44, s46
	s_cselect_b32 s15, s45, s47
	s_add_u32 s14, s14, s28
	s_addc_u32 s15, s15, s29
	s_lshl_b32 s28, s21, 14
	s_xor_b32 s29, s28, 0x4000
	s_add_i32 s29, s53, s29
	global_load_lds_dwordx4 v240, s[40:41]
	s_mov_b32 m0, s29
	s_mulk_i32 s21, 0x6000
	global_load_lds_dwordx4 v241, s[14:15]
	s_add_i32 m0, s29, 0x2000
	s_nop 0
	global_load_lds_dwordx4 v244, s[14:15]
	v_add_u32_e32 v74, s21, v182
	v_add_u32_e32 v75, v74, v181
	ds_read_b128 v[66:69], v75 offset:32768
	v_add_u32_e32 v76, v74, v183
	ds_read_b128 v[70:73], v76 offset:32768
	v_add_u32_e32 v153, v74, v184
	v_add_u32_e32 v155, v74, v185
	v_add_u32_e32 v157, v74, v186
	v_add_u32_e32 v159, v74, v187
	v_add_u32_e32 v209, v74, v188
	v_add_u32_e32 v218, v74, v189
	s_waitcnt lgkmcnt(0)
	v_mfma_f32_32x32x16_bf16 v[82:97], v[66:69], v[142:145], 0
	ds_read_b128 v[66:69], v153 offset:32768
	v_add_u32_e32 v219, v74, v190
	v_add_u32_e32 v220, v74, v191
	v_add_u32_e32 v221, v74, v192
	v_add_u32_e32 v222, v74, v193
	v_mfma_f32_32x32x16_bf16 v[82:97], v[70:73], v[138:141], v[82:97]
	ds_read_b128 v[70:73], v155 offset:32768
	s_waitcnt lgkmcnt(0)
	v_mfma_f32_32x32x16_bf16 v[82:97], v[66:69], v[134:137], v[82:97]
	ds_read_b128 v[66:69], v157 offset:32768
	v_mfma_f32_32x32x16_bf16 v[82:97], v[70:73], v[130:133], v[82:97]
	ds_read_b128 v[70:73], v159 offset:32768
	s_waitcnt lgkmcnt(0)
	v_mfma_f32_32x32x16_bf16 v[82:97], v[66:69], v[126:129], v[82:97]
	ds_read_b128 v[66:69], v209 offset:32768
	v_mfma_f32_32x32x16_bf16 v[82:97], v[70:73], v[122:125], v[82:97]
	ds_read_b128 v[70:73], v218 offset:32768
	s_waitcnt lgkmcnt(0)
	v_mfma_f32_32x32x16_bf16 v[82:97], v[66:69], v[118:121], v[82:97]
	ds_read_b128 v[66:69], v219 offset:32768
	v_mfma_f32_32x32x16_bf16 v[82:97], v[70:73], v[114:117], v[82:97]
	ds_read_b128 v[70:73], v220 offset:32768
	s_waitcnt lgkmcnt(0)
	v_mfma_f32_32x32x16_bf16 v[82:97], v[66:69], v[110:113], v[82:97]
	ds_read_b128 v[66:69], v221 offset:32768
	v_mfma_f32_32x32x16_bf16 v[82:97], v[70:73], v[106:109], v[82:97]
	ds_read_b128 v[70:73], v222 offset:32768
	s_waitcnt lgkmcnt(0)
	v_mfma_f32_32x32x16_bf16 v[82:97], v[66:69], v[102:105], v[82:97]
	v_mfma_f32_32x32x16_bf16 v[82:97], v[70:73], v[98:101], v[82:97]
	ds_read_b128 v[66:69], v75 offset:45056
	ds_read_b128 v[210:213], v76 offset:45056
	s_nop 9
	v_exp_f32_e32 v226, v86
	v_exp_f32_e32 v227, v87
	v_exp_f32_e32 v228, v88
	s_waitcnt lgkmcnt(0)
	v_mfma_f32_32x32x16_bf16 v[66:81], v[66:69], v[142:145], 0
	v_exp_f32_e32 v229, v89
	v_exp_f32_e32 v230, v90
	v_exp_f32_e32 v231, v91
	v_exp_f32_e32 v232, v92
	v_exp_f32_e32 v233, v93
	v_exp_f32_e32 v234, v94
	v_exp_f32_e32 v235, v95
	v_mfma_f32_32x32x16_bf16 v[66:81], v[210:213], v[138:141], v[66:81]
	ds_read_b128 v[210:213], v153 offset:45056
	ds_read_b128 v[214:217], v155 offset:45056
	v_exp_f32_e32 v155, v82
	v_exp_f32_e32 v236, v96
	v_exp_f32_e32 v237, v97
	v_cvt_pk_bf16_f32 v86, v230, v231
	v_cvt_pk_bf16_f32 v87, v232, v233
	v_cvt_pk_bf16_f32 v88, v234, v235
	s_waitcnt lgkmcnt(0)
	v_mfma_f32_32x32x16_bf16 v[66:81], v[210:213], v[134:137], v[66:81]
	v_cvt_pk_bf16_f32 v89, v236, v237
	v_add_u32_e32 v153, s28, v179
	v_mfma_f32_32x32x16_bf16 v[66:81], v[214:217], v[130:133], v[66:81]
	ds_read_b128 v[210:213], v157 offset:45056
	ds_read_b128 v[214:217], v159 offset:45056
	v_exp_f32_e32 v157, v83
	v_exp_f32_e32 v159, v84
	v_cvt_pk_bf16_f32 v84, v226, v227
	v_cvt_pk_bf16_f32 v82, v155, v157
	s_waitcnt lgkmcnt(0)
	v_mfma_f32_32x32x16_bf16 v[66:81], v[210:213], v[126:129], v[66:81]
	v_mfma_f32_32x32x16_bf16 v[66:81], v[214:217], v[122:125], v[66:81]
	ds_read_b128 v[210:213], v209 offset:45056
	ds_read_b128 v[214:217], v218 offset:45056
	v_exp_f32_e32 v209, v85
	v_cvt_pk_bf16_f32 v85, v228, v229
	v_cvt_pk_bf16_f32 v83, v159, v209
	s_waitcnt lgkmcnt(0)
	v_mfma_f32_32x32x16_bf16 v[66:81], v[210:213], v[118:121], v[66:81]
	ds_read_b128 v[210:213], v219 offset:45056
	v_mfma_f32_32x32x16_bf16 v[66:81], v[214:217], v[114:117], v[66:81]
	ds_read_b128 v[214:217], v220 offset:45056
	ds_read_b128 v[218:221], v221 offset:45056
	ds_read_b128 v[222:225], v222 offset:45056
	s_waitcnt lgkmcnt(0)
	v_mfma_f32_32x32x16_bf16 v[66:81], v[210:213], v[110:113], v[66:81]
	v_mfma_f32_32x32x16_bf16 v[66:81], v[214:217], v[106:109], v[66:81]
	v_mfma_f32_32x32x16_bf16 v[66:81], v[218:221], v[102:105], v[66:81]
	v_mfma_f32_32x32x16_bf16 v[66:81], v[222:225], v[98:101], v[66:81]
	ds_read_b64_tr_b16 v[90:91], v153 offset:0
	ds_read_b64_tr_b16 v[92:93], v153 offset:0x800
	ds_read_b64_tr_b16 v[94:95], v153 offset:0x1000
	ds_read_b64_tr_b16 v[96:97], v153 offset:0x1800
	ds_read_b64_tr_b16 v[210:211], v153 offset:0x200
	ds_read_b64_tr_b16 v[212:213], v153 offset:0xa00
	ds_read_b64_tr_b16 v[214:215], v153 offset:0x1200
	ds_read_b64_tr_b16 v[216:217], v153 offset:0x1a00
	s_waitcnt lgkmcnt(4)
	s_nop 0
	v_mfma_f32_32x32x16_bf16 v[2:17], v[82:85], v[90:93], v[2:17]
	s_nop 1
	v_exp_f32_e32 v218, v66
	v_exp_f32_e32 v219, v67
	v_exp_f32_e32 v220, v68
	v_exp_f32_e32 v221, v69
	v_mfma_f32_32x32x16_bf16 v[2:17], v[86:89], v[94:97], v[2:17]
	ds_read_b64_tr_b16 v[66:67], v153 offset:0x400
	ds_read_b64_tr_b16 v[68:69], v153 offset:0xc00
	ds_read_b64_tr_b16 v[90:91], v153 offset:0x1400
	ds_read_b64_tr_b16 v[92:93], v153 offset:0x1c00
	s_waitcnt lgkmcnt(4)
	v_mfma_f32_32x32x16_bf16 v[18:33], v[82:85], v[210:213], v[18:33]
	v_exp_f32_e32 v210, v70
	v_exp_f32_e32 v211, v71
	v_exp_f32_e32 v212, v72
	v_exp_f32_e32 v213, v73
	v_mfma_f32_32x32x16_bf16 v[18:33], v[86:89], v[214:217], v[18:33]
	ds_read_b64_tr_b16 v[70:71], v153 offset:0x600
	ds_read_b64_tr_b16 v[72:73], v153 offset:0xe00
	ds_read_b64_tr_b16 v[94:95], v153 offset:0x1600
	ds_read_b64_tr_b16 v[96:97], v153 offset:0x1e00
	s_waitcnt lgkmcnt(4)
	v_mfma_f32_32x32x16_bf16 v[34:49], v[82:85], v[66:69], v[34:49]
	v_exp_f32_e32 v214, v74
	v_exp_f32_e32 v215, v75
	v_exp_f32_e32 v216, v76
	v_exp_f32_e32 v217, v77
	v_mfma_f32_32x32x16_bf16 v[34:49], v[86:89], v[90:93], v[34:49]
	ds_read_b64_tr_b16 v[66:67], v153 offset:0x2000
	ds_read_b64_tr_b16 v[68:69], v153 offset:0x2800
	ds_read_b64_tr_b16 v[74:75], v153 offset:0x3000
	ds_read_b64_tr_b16 v[76:77], v153 offset:0x3800
	s_waitcnt lgkmcnt(4)
	v_exp_f32_e32 v90, v78
	v_mfma_f32_32x32x16_bf16 v[50:65], v[82:85], v[70:73], v[50:65]
	v_exp_f32_e32 v91, v79
	v_cvt_pk_bf16_f32 v72, v210, v211
	v_cvt_pk_bf16_f32 v73, v212, v213
	v_mfma_f32_32x32x16_bf16 v[50:65], v[86:89], v[94:97], v[50:65]
	v_exp_f32_e32 v92, v80
	v_exp_f32_e32 v248, v81
	v_cvt_pk_bf16_f32 v78, v214, v215
	v_cvt_pk_bf16_f32 v79, v216, v217
	v_cvt_pk_bf16_f32 v80, v90, v91
	v_cvt_pk_bf16_f32 v70, v218, v219
	v_cvt_pk_bf16_f32 v71, v220, v221
	v_cvt_pk_bf16_f32 v81, v92, v248
	ds_read_b64_tr_b16 v[82:83], v153 offset:0x2200
	ds_read_b64_tr_b16 v[84:85], v153 offset:0x2a00
	ds_read_b64_tr_b16 v[86:87], v153 offset:0x3200
	ds_read_b64_tr_b16 v[88:89], v153 offset:0x3a00
	s_waitcnt lgkmcnt(4)
	s_nop 0
	v_mfma_f32_32x32x16_bf16 v[2:17], v[70:73], v[66:69], v[2:17]
	v_add_f32_e32 v246, v155, v157
	v_add_f32_e32 v247, v218, v219
	v_add_f32_e32 v246, v246, v159
	v_add_f32_e32 v247, v247, v220
	v_mfma_f32_32x32x16_bf16 v[2:17], v[78:81], v[74:77], v[2:17]
	v_add_f32_e32 v246, v246, v209
	v_add_f32_e32 v247, v247, v221
	v_add_f32_e32 v246, v246, v226
	v_add_f32_e32 v247, v247, v210
	ds_read_b64_tr_b16 v[66:67], v153 offset:0x2400
	ds_read_b64_tr_b16 v[68:69], v153 offset:0x2c00
	ds_read_b64_tr_b16 v[74:75], v153 offset:0x3400
	ds_read_b64_tr_b16 v[76:77], v153 offset:0x3c00
	s_waitcnt lgkmcnt(4)
	v_mfma_f32_32x32x16_bf16 v[18:33], v[70:73], v[82:85], v[18:33]
	v_add_f32_e32 v246, v246, v227
	v_add_f32_e32 v247, v247, v211
	v_add_f32_e32 v246, v246, v228
	v_add_f32_e32 v247, v247, v212
	v_mfma_f32_32x32x16_bf16 v[18:33], v[78:81], v[86:89], v[18:33]
	v_add_f32_e32 v246, v246, v229
	v_add_f32_e32 v247, v247, v213
	v_add_f32_e32 v246, v246, v230
	v_add_f32_e32 v247, v247, v214
	ds_read_b64_tr_b16 v[82:83], v153 offset:0x2600
	ds_read_b64_tr_b16 v[84:85], v153 offset:0x2e00
	ds_read_b64_tr_b16 v[86:87], v153 offset:0x3600
	ds_read_b64_tr_b16 v[88:89], v153 offset:0x3e00
	s_waitcnt lgkmcnt(4)
	v_mfma_f32_32x32x16_bf16 v[34:49], v[70:73], v[66:69], v[34:49]
	v_add_f32_e32 v246, v246, v231
	v_add_f32_e32 v247, v247, v215
	v_add_f32_e32 v246, v246, v232
	v_add_f32_e32 v247, v247, v216
	v_mfma_f32_32x32x16_bf16 v[34:49], v[78:81], v[74:77], v[34:49]
	v_add_f32_e32 v246, v246, v233
	v_add_f32_e32 v247, v247, v217
	v_add_f32_e32 v246, v246, v234
	v_add_f32_e32 v247, v247, v90
	s_waitcnt lgkmcnt(0)
	v_mfma_f32_32x32x16_bf16 v[50:65], v[70:73], v[82:85], v[50:65]
	v_add_f32_e32 v246, v246, v235
	v_add_f32_e32 v247, v247, v91
	v_add_f32_e32 v246, v246, v236
	v_add_f32_e32 v247, v247, v92
	v_add_f32_e32 v246, v246, v237
	v_add_f32_e32 v247, v247, v248
	v_add_f32_e32 v246, v246, v247
	v_add_f32_e32 v151, v151, v246
	s_waitcnt vmcnt(0)
	s_add_u32 s0, s0, 64
	s_addc_u32 s1, s1, 0
	s_add_i32 s4, s4, 1
	s_cmpk_eq_i32 s0, 0x4100
	s_waitcnt vmcnt(0)
	s_barrier
	v_mfma_f32_32x32x16_bf16 v[50:65], v[78:81], v[86:89], v[50:65]
	s_cbranch_scc0 .LBB0_2312
	s_lshl_b32 s0, s52, 2
	s_add_i32 s4, s0, 0
	s_add_i32 s4, s4, 0x1e000
	ds_read_b128 v[66:69], v196
	ds_read_b128 v[70:73], v197
	s_waitcnt lgkmcnt(1)
	v_mfma_f32_32x32x16_bf16 v[82:97], v[66:69], v[142:145], 0
	s_waitcnt lgkmcnt(0)
	v_mfma_f32_32x32x16_bf16 v[82:97], v[70:73], v[138:141], v[82:97]
	ds_read_b128 v[66:69], v198
	ds_read_b128 v[70:73], v199
	s_waitcnt lgkmcnt(1)
	v_mfma_f32_32x32x16_bf16 v[82:97], v[66:69], v[134:137], v[82:97]
	s_waitcnt lgkmcnt(0)
	v_mfma_f32_32x32x16_bf16 v[82:97], v[70:73], v[130:133], v[82:97]
	ds_read_b128 v[66:69], v200
	ds_read_b128 v[70:73], v201
	s_waitcnt lgkmcnt(1)
	v_mfma_f32_32x32x16_bf16 v[82:97], v[66:69], v[126:129], v[82:97]
	s_waitcnt lgkmcnt(0)
	v_mfma_f32_32x32x16_bf16 v[82:97], v[70:73], v[122:125], v[82:97]
	ds_read_b128 v[66:69], v202
	ds_read_b128 v[70:73], v203
	s_waitcnt lgkmcnt(1)
	v_mfma_f32_32x32x16_bf16 v[82:97], v[66:69], v[118:121], v[82:97]
	s_waitcnt lgkmcnt(0)
	v_mfma_f32_32x32x16_bf16 v[82:97], v[70:73], v[114:117], v[82:97]
	ds_read_b128 v[66:69], v204
	ds_read_b128 v[70:73], v205
	s_waitcnt lgkmcnt(1)
	v_mfma_f32_32x32x16_bf16 v[82:97], v[66:69], v[110:113], v[82:97]
	s_waitcnt lgkmcnt(0)
	v_mfma_f32_32x32x16_bf16 v[82:97], v[70:73], v[106:109], v[82:97]
	ds_read_b128 v[66:69], v206
	ds_read_b128 v[70:73], v207
	s_waitcnt lgkmcnt(1)
	v_mfma_f32_32x32x16_bf16 v[82:97], v[66:69], v[102:105], v[82:97]
	s_waitcnt lgkmcnt(0)
	v_mfma_f32_32x32x16_bf16 v[82:97], v[70:73], v[98:101], v[82:97]
	ds_read_b128 v[66:69], v196 offset:12288
	ds_read_b128 v[160:163], v197 offset:12288
	s_waitcnt lgkmcnt(1)
	v_mfma_f32_32x32x16_bf16 v[66:81], v[66:69], v[142:145], 0
	s_waitcnt lgkmcnt(0)
	v_mfma_f32_32x32x16_bf16 v[66:81], v[160:163], v[138:141], v[66:81]
	ds_read_b128 v[138:141], v198 offset:12288
	ds_read_b128 v[142:145], v199 offset:12288
	s_waitcnt lgkmcnt(1)
	v_mfma_f32_32x32x16_bf16 v[66:81], v[138:141], v[134:137], v[66:81]
	s_waitcnt lgkmcnt(0)
	v_mfma_f32_32x32x16_bf16 v[66:81], v[142:145], v[130:133], v[66:81]
	ds_read_b128 v[130:133], v200 offset:12288
	ds_read_b128 v[134:137], v201 offset:12288
	s_waitcnt lgkmcnt(1)
	v_mfma_f32_32x32x16_bf16 v[66:81], v[130:133], v[126:129], v[66:81]
	v_exp_f32_e32 v130, v82
	v_exp_f32_e32 v131, v83
	v_exp_f32_e32 v132, v84
	v_cvt_pk_bf16_f32 v82, v130, v131
	s_waitcnt lgkmcnt(0)
	v_mfma_f32_32x32x16_bf16 v[66:81], v[134:137], v[122:125], v[66:81]
	ds_read_b128 v[122:125], v202 offset:12288
	ds_read_b128 v[126:129], v203 offset:12288
	s_waitcnt lgkmcnt(1)
	v_mfma_f32_32x32x16_bf16 v[66:81], v[122:125], v[118:121], v[66:81]
	s_waitcnt lgkmcnt(0)
	v_mfma_f32_32x32x16_bf16 v[66:81], v[126:129], v[114:117], v[66:81]
	ds_read_b128 v[114:117], v204 offset:12288
	ds_read_b128 v[118:121], v205 offset:12288
	ds_read_b128 v[122:125], v206 offset:12288
	ds_read_b128 v[126:129], v207 offset:12288
	s_waitcnt lgkmcnt(3)
	v_mfma_f32_32x32x16_bf16 v[66:81], v[114:117], v[110:113], v[66:81]
	v_exp_f32_e32 v110, v85
	v_exp_f32_e32 v111, v86
	v_exp_f32_e32 v112, v87
	v_exp_f32_e32 v113, v88
	v_exp_f32_e32 v114, v89
	v_exp_f32_e32 v115, v90
	v_exp_f32_e32 v116, v91
	s_waitcnt lgkmcnt(2)
	v_mfma_f32_32x32x16_bf16 v[66:81], v[118:121], v[106:109], v[66:81]
	v_exp_f32_e32 v106, v92
	v_exp_f32_e32 v107, v93
	v_exp_f32_e32 v108, v94
	v_exp_f32_e32 v109, v95
	v_exp_f32_e32 v117, v96
	v_exp_f32_e32 v118, v97
	v_cvt_pk_bf16_f32 v83, v132, v110
	s_waitcnt lgkmcnt(1)
	v_mfma_f32_32x32x16_bf16 v[66:81], v[122:125], v[102:105], v[66:81]
	v_cvt_pk_bf16_f32 v84, v111, v112
	v_cvt_pk_bf16_f32 v85, v113, v114
	v_cvt_pk_bf16_f32 v86, v115, v116
	v_cvt_pk_bf16_f32 v87, v106, v107
	v_cvt_pk_bf16_f32 v88, v108, v109
	v_cvt_pk_bf16_f32 v89, v117, v118
	s_waitcnt lgkmcnt(0)
	v_mfma_f32_32x32x16_bf16 v[66:81], v[126:129], v[98:101], v[66:81]
	ds_read_b64_tr_b16 v[90:91], v208 offset:0
	ds_read_b64_tr_b16 v[92:93], v208 offset:0x800
	ds_read_b64_tr_b16 v[94:95], v208 offset:0x1000
	ds_read_b64_tr_b16 v[96:97], v208 offset:0x1800
	ds_read_b64_tr_b16 v[98:99], v208 offset:0x200
	ds_read_b64_tr_b16 v[100:101], v208 offset:0xa00
	ds_read_b64_tr_b16 v[102:103], v208 offset:0x1200
	ds_read_b64_tr_b16 v[104:105], v208 offset:0x1a00
	s_waitcnt lgkmcnt(4)
	s_nop 0
	v_mfma_f32_32x32x16_bf16 v[2:17], v[82:85], v[90:93], v[2:17]
	s_nop 6
	v_exp_f32_e32 v119, v66
	v_exp_f32_e32 v120, v67
	v_exp_f32_e32 v121, v68
	v_exp_f32_e32 v122, v69
	v_mfma_f32_32x32x16_bf16 v[2:17], v[86:89], v[94:97], v[2:17]
	ds_read_b64_tr_b16 v[66:67], v208 offset:0x400
	ds_read_b64_tr_b16 v[68:69], v208 offset:0xc00
	ds_read_b64_tr_b16 v[90:91], v208 offset:0x1400
	ds_read_b64_tr_b16 v[92:93], v208 offset:0x1c00
	s_waitcnt lgkmcnt(4)
	v_mfma_f32_32x32x16_bf16 v[18:33], v[82:85], v[98:101], v[18:33]
	v_exp_f32_e32 v98, v70
	v_exp_f32_e32 v99, v71
	v_exp_f32_e32 v100, v72
	v_exp_f32_e32 v101, v73
	v_mfma_f32_32x32x16_bf16 v[18:33], v[86:89], v[102:105], v[18:33]
	ds_read_b64_tr_b16 v[70:71], v208 offset:0x600
	ds_read_b64_tr_b16 v[72:73], v208 offset:0xe00
	ds_read_b64_tr_b16 v[94:95], v208 offset:0x1600
	ds_read_b64_tr_b16 v[96:97], v208 offset:0x1e00
	s_waitcnt lgkmcnt(4)
	v_mfma_f32_32x32x16_bf16 v[34:49], v[82:85], v[66:69], v[34:49]
	v_exp_f32_e32 v102, v74
	v_exp_f32_e32 v103, v75
	v_exp_f32_e32 v104, v76
	v_exp_f32_e32 v105, v77
	v_mfma_f32_32x32x16_bf16 v[34:49], v[86:89], v[90:93], v[34:49]
	ds_read_b64_tr_b16 v[74:75], v208 offset:0x2000
	ds_read_b64_tr_b16 v[76:77], v208 offset:0x2800
	ds_read_b64_tr_b16 v[90:91], v208 offset:0x3000
	ds_read_b64_tr_b16 v[92:93], v208 offset:0x3800
	s_waitcnt lgkmcnt(4)
	v_add_f32_e32 v66, v130, v131
	v_add_f32_e32 v67, v119, v120
	v_mfma_f32_32x32x16_bf16 v[50:65], v[82:85], v[70:73], v[50:65]
	v_add_f32_e32 v66, v66, v132
	v_add_f32_e32 v67, v67, v121
	v_exp_f32_e32 v123, v78
	v_add_f32_e32 v66, v66, v110
	v_add_f32_e32 v67, v67, v122
	v_exp_f32_e32 v124, v79
	v_add_f32_e32 v66, v66, v111
	v_add_f32_e32 v67, v67, v98
	v_mfma_f32_32x32x16_bf16 v[50:65], v[86:89], v[94:97], v[50:65]
	v_add_f32_e32 v66, v66, v112
	v_add_f32_e32 v67, v67, v99
	v_exp_f32_e32 v125, v80
	v_add_f32_e32 v66, v66, v113
	v_add_f32_e32 v67, v67, v100
	v_exp_f32_e32 v81, v81
	v_add_f32_e32 v66, v66, v114
	v_add_f32_e32 v67, v67, v101
	v_cvt_pk_bf16_f32 v68, v119, v120
	v_add_f32_e32 v66, v66, v115
	v_add_f32_e32 v67, v67, v102
	v_cvt_pk_bf16_f32 v69, v121, v122
	v_add_f32_e32 v66, v66, v116
	v_add_f32_e32 v67, v67, v103
	v_cvt_pk_bf16_f32 v70, v98, v99
	v_add_f32_e32 v66, v66, v106
	v_add_f32_e32 v67, v67, v104
	v_cvt_pk_bf16_f32 v71, v100, v101
	v_add_f32_e32 v66, v66, v107
	v_add_f32_e32 v67, v67, v105
	v_cvt_pk_bf16_f32 v78, v102, v103
	v_add_f32_e32 v66, v66, v108
	v_add_f32_e32 v67, v67, v123
	v_cvt_pk_bf16_f32 v79, v104, v105
	v_add_f32_e32 v66, v66, v109
	v_add_f32_e32 v67, v67, v124
	v_cvt_pk_bf16_f32 v80, v123, v124
	v_add_f32_e32 v66, v66, v117
	v_add_f32_e32 v67, v67, v125
	v_add_f32_e32 v66, v66, v118
	v_add_f32_e32 v67, v67, v81
	v_cvt_pk_bf16_f32 v81, v125, v81
	v_add_f32_e32 v66, v66, v67
	v_add_f32_e32 v66, v151, v66
	v_mov_b32_e32 v67, v66
	s_nop 1
	v_permlane32_swap_b32_e32 v66, v67
	ds_read_b64_tr_b16 v[82:83], v208 offset:0x2200
	ds_read_b64_tr_b16 v[84:85], v208 offset:0x2a00
	ds_read_b64_tr_b16 v[86:87], v208 offset:0x3200
	ds_read_b64_tr_b16 v[88:89], v208 offset:0x3a00
	s_waitcnt lgkmcnt(4)
	v_mfma_f32_32x32x16_bf16 v[2:17], v[68:71], v[74:77], v[2:17]
	s_nop 0
	v_mfma_f32_32x32x16_bf16 v[2:17], v[78:81], v[90:93], v[2:17]
	ds_read_b64_tr_b16 v[72:73], v208 offset:0x2400
	ds_read_b64_tr_b16 v[74:75], v208 offset:0x2c00
	ds_read_b64_tr_b16 v[90:91], v208 offset:0x3400
	ds_read_b64_tr_b16 v[92:93], v208 offset:0x3c00
	s_waitcnt lgkmcnt(4)
	v_mfma_f32_32x32x16_bf16 v[18:33], v[68:71], v[82:85], v[18:33]
	v_mfma_f32_32x32x16_bf16 v[18:33], v[78:81], v[86:89], v[18:33]
	ds_read_b64_tr_b16 v[82:83], v208 offset:0x2600
	ds_read_b64_tr_b16 v[84:85], v208 offset:0x2e00
	ds_read_b64_tr_b16 v[86:87], v208 offset:0x3600
	ds_read_b64_tr_b16 v[88:89], v208 offset:0x3e00
	s_waitcnt lgkmcnt(4)
	v_mfma_f32_32x32x16_bf16 v[34:49], v[68:71], v[72:75], v[34:49]
	v_mfma_f32_32x32x16_bf16 v[34:49], v[78:81], v[90:93], v[34:49]
	s_waitcnt lgkmcnt(0)
	v_mfma_f32_32x32x16_bf16 v[50:65], v[68:71], v[82:85], v[50:65]
	s_waitcnt vmcnt(0)
	s_barrier
	v_mfma_f32_32x32x16_bf16 v[50:65], v[78:81], v[86:89], v[50:65]
	s_and_saveexec_b64 s[0:1], s[2:3]
	s_cbranch_execz .LBB0_2310
	v_add_f32_e32 v66, v66, v67
	v_lshl_add_u32 v68, v165, 2, s4
	ds_write_b32 v68, v66
	s_branch .LBB0_2310
